# GEMM main loop back-edge: pointer bumps moved in front of the loop-back barrier, load-segment heads issue their LDS reads first (literal address adds) with the scalar bookkeeping sunk below the read b
# speedup vs baseline: 1.0005x; 1.0005x over previous
.LBB0_2002:
	v_add_u32_e32 v154, 0x10000, v162
	v_add_u32_e32 v180, 0x14000, v162
	ds_read_b128 v[130:133], v154
	ds_read_b128 v[134:137], v154 offset:1024
	ds_read_b128 v[150:153], v154 offset:2048
	ds_read_b128 v[154:157], v154 offset:3072
	ds_read_b128 v[168:171], v180
	ds_read_b128 v[172:175], v180 offset:1024
	ds_read_b128 v[176:179], v180 offset:2048
	ds_read_b128 v[180:183], v180 offset:3072
	v_lshl_add_u64 v[200:201], s[2:3], 0, v[148:149]
	s_add_i32 m0, s61, 0xc000
	ds_read_b128 v[184:187], v167
	ds_read_b128 v[188:191], v167 offset:1024
	ds_read_b128 v[192:195], v167 offset:2048
	ds_read_b128 v[196:199], v167 offset:3072
	ds_read_b128 v[220:223], v167 offset:4096
	ds_read_b128 v[224:227], v167 offset:5120
	ds_read_b128 v[228:231], v167 offset:6144
	ds_read_b128 v[232:235], v167 offset:7168
	global_load_lds_dwordx4 v[200:201], off
	v_lshl_add_u64 v[200:201], s[2:3], 0, v[146:147]
	s_add_i32 m0, s61, 0xe000
	s_nop 0
	global_load_lds_dwordx4 v[200:201], off
	s_add_i32 s72, s51, 2
	s_add_u32 s24, s2, 0x80
	s_addc_u32 s25, s3, 0
	s_add_i32 s73, 0, 0x10000
	s_cmp_eq_u32 s31, s51
	s_cselect_b32 s25, s45, s25
	s_cselect_b32 s24, s44, s24
	s_cselect_b32 vcc_hi, s39, s71
	s_cselect_b32 vcc_lo, s38, s11
	s_add_i32 s51, 0, 0x14000
	s_waitcnt vmcnt(8)
	s_waitcnt lgkmcnt(0)
	s_barrier
	s_setprio 1
	s_waitcnt lgkmcnt(0)
	v_mfma_f32_16x16x32_bf16 v[122:125], v[130:133], v[184:187], v[122:125]
	v_mfma_f32_16x16x32_bf16 v[118:121], v[150:153], v[184:187], v[118:121]
	v_mfma_f32_16x16x32_bf16 v[102:105], v[130:133], v[192:195], v[102:105]
	v_mfma_f32_16x16x32_bf16 v[98:101], v[150:153], v[192:195], v[98:101]
	v_mfma_f32_16x16x32_bf16 v[86:89], v[130:133], v[220:223], v[86:89]
	v_mfma_f32_16x16x32_bf16 v[82:85], v[150:153], v[220:223], v[82:85]
	v_mfma_f32_16x16x32_bf16 v[70:73], v[130:133], v[228:231], v[70:73]
	v_mfma_f32_16x16x32_bf16 v[66:69], v[150:153], v[228:231], v[66:69]
	v_mfma_f32_16x16x32_bf16 v[122:125], v[134:137], v[188:191], v[122:125]
	v_mfma_f32_16x16x32_bf16 v[118:121], v[154:157], v[188:191], v[118:121]
	v_mfma_f32_16x16x32_bf16 v[102:105], v[134:137], v[196:199], v[102:105]
	v_mfma_f32_16x16x32_bf16 v[98:101], v[154:157], v[196:199], v[98:101]
	v_mfma_f32_16x16x32_bf16 v[86:89], v[134:137], v[224:227], v[86:89]
	v_mfma_f32_16x16x32_bf16 v[82:85], v[154:157], v[224:227], v[82:85]
	v_mfma_f32_16x16x32_bf16 v[70:73], v[134:137], v[232:235], v[70:73]
	v_mfma_f32_16x16x32_bf16 v[66:69], v[154:157], v[232:235], v[66:69]
	s_setprio 0
	s_setprio 1
	v_mfma_f32_16x16x32_bf16 v[114:117], v[168:171], v[184:187], v[114:117]
	v_mfma_f32_16x16x32_bf16 v[126:129], v[176:179], v[184:187], v[126:129]
	v_mfma_f32_16x16x32_bf16 v[110:113], v[168:171], v[192:195], v[110:113]
	v_mfma_f32_16x16x32_bf16 v[106:109], v[176:179], v[192:195], v[106:109]
	v_mfma_f32_16x16x32_bf16 v[94:97], v[168:171], v[220:223], v[94:97]
	v_mfma_f32_16x16x32_bf16 v[90:93], v[176:179], v[220:223], v[90:93]
	v_mfma_f32_16x16x32_bf16 v[78:81], v[168:171], v[228:231], v[78:81]
	v_mfma_f32_16x16x32_bf16 v[74:77], v[176:179], v[228:231], v[74:77]
	v_mfma_f32_16x16x32_bf16 v[114:117], v[172:175], v[188:191], v[114:117]
	v_mfma_f32_16x16x32_bf16 v[126:129], v[180:183], v[188:191], v[126:129]
	v_mfma_f32_16x16x32_bf16 v[110:113], v[172:175], v[196:199], v[110:113]
	v_mfma_f32_16x16x32_bf16 v[106:109], v[180:183], v[196:199], v[106:109]
	v_mfma_f32_16x16x32_bf16 v[94:97], v[172:175], v[224:227], v[94:97]
	v_mfma_f32_16x16x32_bf16 v[90:93], v[180:183], v[224:227], v[90:93]
	v_mfma_f32_16x16x32_bf16 v[78:81], v[172:175], v[232:235], v[78:81]
	v_mfma_f32_16x16x32_bf16 v[74:77], v[180:183], v[232:235], v[74:77]
	s_setprio 0
	s_barrier
	ds_read_b128 v[184:187], v167 offset:16384
	ds_read_b128 v[188:191], v167 offset:17408
	ds_read_b128 v[192:195], v167 offset:18432
	ds_read_b128 v[196:199], v167 offset:19456
	ds_read_b128 v[220:223], v167 offset:20480
	ds_read_b128 v[224:227], v167 offset:21504
	ds_read_b128 v[228:231], v167 offset:22528
	ds_read_b128 v[232:235], v167 offset:23552
	s_add_i32 s73, s73, s75
	v_lshl_add_u64 v[200:201], vcc, 0, v[0:1]
	s_mov_b32 m0, s73
	s_nop 0
	global_load_lds_dwordx4 v[200:201], off
	s_add_i32 m0, s73, 0x2000
	v_lshl_add_u64 v[236:237], vcc, 0, v[144:145]
	s_add_u32 vcc_lo, vcc_lo, s46
	s_addc_u32 vcc_hi, vcc_hi, 0
	s_add_i32 s51, s51, s75
	global_load_lds_dwordx4 v[236:237], off
	v_lshl_add_u64 v[238:239], vcc, 0, v[0:1]
	s_mov_b32 m0, s51
	v_lshl_add_u64 v[240:241], vcc, 0, v[144:145]
	global_load_lds_dwordx4 v[238:239], off
	s_add_i32 m0, s51, 0x2000
	v_lshl_add_u64 v[242:243], s[24:25], 0, v[140:141]
	global_load_lds_dwordx4 v[240:241], off
	s_mov_b32 m0, s61
	v_lshl_add_u64 v[244:245], s[24:25], 0, v[142:143]
	global_load_lds_dwordx4 v[242:243], off
	s_mov_b32 m0, s76
	s_nop 0
	global_load_lds_dwordx4 v[244:245], off
	s_waitcnt vmcnt(8)
	s_waitcnt lgkmcnt(0)
	s_barrier
	s_setprio 1
	s_waitcnt lgkmcnt(0)
	v_mfma_f32_16x16x32_bf16 v[54:57], v[130:133], v[184:187], v[54:57]
	v_mfma_f32_16x16x32_bf16 v[50:53], v[150:153], v[184:187], v[50:53]
	v_mfma_f32_16x16x32_bf16 v[42:45], v[130:133], v[192:195], v[42:45]
	v_mfma_f32_16x16x32_bf16 v[38:41], v[150:153], v[192:195], v[38:41]
	v_mfma_f32_16x16x32_bf16 v[30:33], v[130:133], v[220:223], v[30:33]
	v_mfma_f32_16x16x32_bf16 v[26:29], v[150:153], v[220:223], v[26:29]
	v_mfma_f32_16x16x32_bf16 v[14:17], v[130:133], v[228:231], v[14:17]
	v_mfma_f32_16x16x32_bf16 v[10:13], v[150:153], v[228:231], v[10:13]
	v_mfma_f32_16x16x32_bf16 v[54:57], v[134:137], v[188:191], v[54:57]
	v_mfma_f32_16x16x32_bf16 v[50:53], v[154:157], v[188:191], v[50:53]
	v_mfma_f32_16x16x32_bf16 v[42:45], v[134:137], v[196:199], v[42:45]
	v_mfma_f32_16x16x32_bf16 v[38:41], v[154:157], v[196:199], v[38:41]
	v_mfma_f32_16x16x32_bf16 v[30:33], v[134:137], v[224:227], v[30:33]
	v_mfma_f32_16x16x32_bf16 v[26:29], v[154:157], v[224:227], v[26:29]
	v_mfma_f32_16x16x32_bf16 v[14:17], v[134:137], v[232:235], v[14:17]
	v_mfma_f32_16x16x32_bf16 v[10:13], v[154:157], v[232:235], v[10:13]
	s_setprio 0
	s_setprio 1
	v_mfma_f32_16x16x32_bf16 v[62:65], v[168:171], v[184:187], v[62:65]
	v_mfma_f32_16x16x32_bf16 v[58:61], v[176:179], v[184:187], v[58:61]
	v_mfma_f32_16x16x32_bf16 v[46:49], v[168:171], v[192:195], v[46:49]
	v_mfma_f32_16x16x32_bf16 v[34:37], v[176:179], v[192:195], v[34:37]
	v_mfma_f32_16x16x32_bf16 v[22:25], v[168:171], v[220:223], v[22:25]
	v_mfma_f32_16x16x32_bf16 v[18:21], v[176:179], v[220:223], v[18:21]
	v_mfma_f32_16x16x32_bf16 v[6:9], v[168:171], v[228:231], v[6:9]
	v_mfma_f32_16x16x32_bf16 v[2:5], v[176:179], v[228:231], v[2:5]
	v_mfma_f32_16x16x32_bf16 v[62:65], v[172:175], v[188:191], v[62:65]
	v_mfma_f32_16x16x32_bf16 v[58:61], v[180:183], v[188:191], v[58:61]
	v_mfma_f32_16x16x32_bf16 v[46:49], v[172:175], v[196:199], v[46:49]
	v_mfma_f32_16x16x32_bf16 v[34:37], v[180:183], v[196:199], v[34:37]
	v_mfma_f32_16x16x32_bf16 v[22:25], v[172:175], v[224:227], v[22:25]
	v_mfma_f32_16x16x32_bf16 v[18:21], v[180:183], v[224:227], v[18:21]
	v_mfma_f32_16x16x32_bf16 v[6:9], v[172:175], v[232:235], v[6:9]
	v_mfma_f32_16x16x32_bf16 v[2:5], v[180:183], v[232:235], v[2:5]
	s_setprio 0
	s_barrier
	v_add_u32_e32 v154, 0x18000, v162
	v_add_u32_e32 v180, 0x1c000, v162
	ds_read_b128 v[130:133], v154
	ds_read_b128 v[134:137], v154 offset:1024
	ds_read_b128 v[150:153], v154 offset:2048
	ds_read_b128 v[154:157], v154 offset:3072
	ds_read_b128 v[168:171], v180
	ds_read_b128 v[172:175], v180 offset:1024
	ds_read_b128 v[176:179], v180 offset:2048
	ds_read_b128 v[180:183], v180 offset:3072
	s_add_i32 s51, 0, 0x18000
	s_add_i32 s73, 0, 0x1c000
	s_add_u32 s24, s24, s46
	s_addc_u32 s25, s25, 0
	s_mov_b32 m0, s77
	v_lshl_add_u64 v[246:247], s[24:25], 0, v[140:141]
	ds_read_b128 v[184:187], v167 offset:32768
	ds_read_b128 v[188:191], v167 offset:33792
	ds_read_b128 v[192:195], v167 offset:34816
	ds_read_b128 v[196:199], v167 offset:35840
	ds_read_b128 v[220:223], v167 offset:36864
	ds_read_b128 v[224:227], v167 offset:37888
	ds_read_b128 v[228:231], v167 offset:38912
	ds_read_b128 v[232:235], v167 offset:39936
	global_load_lds_dwordx4 v[246:247], off
	v_lshl_add_u64 v[246:247], s[24:25], 0, v[142:143]
	s_mov_b32 m0, s28
	s_nop 0
	global_load_lds_dwordx4 v[246:247], off
	s_waitcnt vmcnt(8)
	s_waitcnt lgkmcnt(0)
	s_barrier
	s_setprio 1
	s_waitcnt lgkmcnt(0)
	v_mfma_f32_16x16x32_bf16 v[122:125], v[130:133], v[184:187], v[122:125]
	v_mfma_f32_16x16x32_bf16 v[118:121], v[150:153], v[184:187], v[118:121]
	v_mfma_f32_16x16x32_bf16 v[102:105], v[130:133], v[192:195], v[102:105]
	v_mfma_f32_16x16x32_bf16 v[98:101], v[150:153], v[192:195], v[98:101]
	v_mfma_f32_16x16x32_bf16 v[86:89], v[130:133], v[220:223], v[86:89]
	v_mfma_f32_16x16x32_bf16 v[82:85], v[150:153], v[220:223], v[82:85]
	v_mfma_f32_16x16x32_bf16 v[70:73], v[130:133], v[228:231], v[70:73]
	v_mfma_f32_16x16x32_bf16 v[66:69], v[150:153], v[228:231], v[66:69]
	v_mfma_f32_16x16x32_bf16 v[122:125], v[134:137], v[188:191], v[122:125]
	v_mfma_f32_16x16x32_bf16 v[118:121], v[154:157], v[188:191], v[118:121]
	v_mfma_f32_16x16x32_bf16 v[102:105], v[134:137], v[196:199], v[102:105]
	v_mfma_f32_16x16x32_bf16 v[98:101], v[154:157], v[196:199], v[98:101]
	v_mfma_f32_16x16x32_bf16 v[86:89], v[134:137], v[224:227], v[86:89]
	v_mfma_f32_16x16x32_bf16 v[82:85], v[154:157], v[224:227], v[82:85]
	v_mfma_f32_16x16x32_bf16 v[70:73], v[134:137], v[232:235], v[70:73]
	v_mfma_f32_16x16x32_bf16 v[66:69], v[154:157], v[232:235], v[66:69]
	s_setprio 0
	s_setprio 1
	v_mfma_f32_16x16x32_bf16 v[114:117], v[168:171], v[184:187], v[114:117]
	v_mfma_f32_16x16x32_bf16 v[126:129], v[176:179], v[184:187], v[126:129]
	v_mfma_f32_16x16x32_bf16 v[110:113], v[168:171], v[192:195], v[110:113]
	v_mfma_f32_16x16x32_bf16 v[106:109], v[176:179], v[192:195], v[106:109]
	v_mfma_f32_16x16x32_bf16 v[94:97], v[168:171], v[220:223], v[94:97]
	v_mfma_f32_16x16x32_bf16 v[90:93], v[176:179], v[220:223], v[90:93]
	v_mfma_f32_16x16x32_bf16 v[78:81], v[168:171], v[228:231], v[78:81]
	v_mfma_f32_16x16x32_bf16 v[74:77], v[176:179], v[228:231], v[74:77]
	v_mfma_f32_16x16x32_bf16 v[114:117], v[172:175], v[188:191], v[114:117]
	v_mfma_f32_16x16x32_bf16 v[126:129], v[180:183], v[188:191], v[126:129]
	v_mfma_f32_16x16x32_bf16 v[110:113], v[172:175], v[196:199], v[110:113]
	v_mfma_f32_16x16x32_bf16 v[106:109], v[180:183], v[196:199], v[106:109]
	v_mfma_f32_16x16x32_bf16 v[94:97], v[172:175], v[224:227], v[94:97]
	v_mfma_f32_16x16x32_bf16 v[90:93], v[180:183], v[224:227], v[90:93]
	v_mfma_f32_16x16x32_bf16 v[78:81], v[172:175], v[232:235], v[78:81]
	v_mfma_f32_16x16x32_bf16 v[74:77], v[180:183], v[232:235], v[74:77]
	s_setprio 0
	s_barrier
	ds_read_b128 v[184:187], v167 offset:49152
	ds_read_b128 v[188:191], v167 offset:50176
	ds_read_b128 v[192:195], v167 offset:51200
	ds_read_b128 v[196:199], v167 offset:52224
	ds_read_b128 v[220:223], v167 offset:53248
	ds_read_b128 v[224:227], v167 offset:54272
	ds_read_b128 v[228:231], v167 offset:55296
	ds_read_b128 v[232:235], v167 offset:56320
	s_add_i32 s24, s51, s75
	v_lshl_add_u64 v[200:201], v[200:201], 0, s[64:65]
	s_mov_b32 m0, s24
	s_nop 0
	global_load_lds_dwordx4 v[200:201], off
	v_lshl_add_u64 v[200:201], v[236:237], 0, s[64:65]
	s_add_i32 m0, s24, 0x2000
	s_add_i32 s24, s73, s75
	global_load_lds_dwordx4 v[200:201], off
	v_lshl_add_u64 v[200:201], v[238:239], 0, s[64:65]
	s_mov_b32 m0, s24
	s_nop 0
	global_load_lds_dwordx4 v[200:201], off
	v_lshl_add_u64 v[200:201], v[240:241], 0, s[64:65]
	s_add_i32 m0, s24, 0x2000
	s_nop 0
	global_load_lds_dwordx4 v[200:201], off
	v_lshl_add_u64 v[200:201], v[242:243], 0, s[64:65]
	s_mov_b32 m0, s29
	s_nop 0
	global_load_lds_dwordx4 v[200:201], off
	v_lshl_add_u64 v[200:201], v[244:245], 0, s[64:65]
	s_mov_b32 m0, s19
	s_nop 0
	global_load_lds_dwordx4 v[200:201], off
	s_waitcnt vmcnt(8)
	s_waitcnt lgkmcnt(0)
	s_barrier
	s_setprio 1
	s_waitcnt lgkmcnt(0)
	v_mfma_f32_16x16x32_bf16 v[54:57], v[130:133], v[184:187], v[54:57]
	v_mfma_f32_16x16x32_bf16 v[50:53], v[150:153], v[184:187], v[50:53]
	v_mfma_f32_16x16x32_bf16 v[42:45], v[130:133], v[192:195], v[42:45]
	v_mfma_f32_16x16x32_bf16 v[38:41], v[150:153], v[192:195], v[38:41]
	v_mfma_f32_16x16x32_bf16 v[30:33], v[130:133], v[220:223], v[30:33]
	v_mfma_f32_16x16x32_bf16 v[26:29], v[150:153], v[220:223], v[26:29]
	v_mfma_f32_16x16x32_bf16 v[14:17], v[130:133], v[228:231], v[14:17]
	v_mfma_f32_16x16x32_bf16 v[10:13], v[150:153], v[228:231], v[10:13]
	v_mfma_f32_16x16x32_bf16 v[54:57], v[134:137], v[188:191], v[54:57]
	v_mfma_f32_16x16x32_bf16 v[50:53], v[154:157], v[188:191], v[50:53]
	v_mfma_f32_16x16x32_bf16 v[42:45], v[134:137], v[196:199], v[42:45]
	v_mfma_f32_16x16x32_bf16 v[38:41], v[154:157], v[196:199], v[38:41]
	v_mfma_f32_16x16x32_bf16 v[30:33], v[134:137], v[224:227], v[30:33]
	v_mfma_f32_16x16x32_bf16 v[26:29], v[154:157], v[224:227], v[26:29]
	v_mfma_f32_16x16x32_bf16 v[14:17], v[134:137], v[232:235], v[14:17]
	v_mfma_f32_16x16x32_bf16 v[10:13], v[154:157], v[232:235], v[10:13]
	s_setprio 0
	s_setprio 1
	v_mfma_f32_16x16x32_bf16 v[62:65], v[168:171], v[184:187], v[62:65]
	v_mfma_f32_16x16x32_bf16 v[58:61], v[176:179], v[184:187], v[58:61]
	v_mfma_f32_16x16x32_bf16 v[46:49], v[168:171], v[192:195], v[46:49]
	v_mfma_f32_16x16x32_bf16 v[34:37], v[176:179], v[192:195], v[34:37]
	v_mfma_f32_16x16x32_bf16 v[22:25], v[168:171], v[220:223], v[22:25]
	v_mfma_f32_16x16x32_bf16 v[18:21], v[176:179], v[220:223], v[18:21]
	v_mfma_f32_16x16x32_bf16 v[6:9], v[168:171], v[228:231], v[6:9]
	v_mfma_f32_16x16x32_bf16 v[2:5], v[176:179], v[228:231], v[2:5]
	v_mfma_f32_16x16x32_bf16 v[62:65], v[172:175], v[188:191], v[62:65]
	v_mfma_f32_16x16x32_bf16 v[58:61], v[180:183], v[188:191], v[58:61]
	v_mfma_f32_16x16x32_bf16 v[46:49], v[172:175], v[196:199], v[46:49]
	v_mfma_f32_16x16x32_bf16 v[34:37], v[180:183], v[196:199], v[34:37]
	v_mfma_f32_16x16x32_bf16 v[22:25], v[172:175], v[224:227], v[22:25]
	v_mfma_f32_16x16x32_bf16 v[18:21], v[180:183], v[224:227], v[18:21]
	v_mfma_f32_16x16x32_bf16 v[6:9], v[172:175], v[232:235], v[6:9]
	v_mfma_f32_16x16x32_bf16 v[2:5], v[180:183], v[232:235], v[2:5]
	s_setprio 0
	s_add_u32 s11, s11, 0x100
	s_addc_u32 s71, s71, 0
	s_add_u32 s2, s2, 0x100
	s_addc_u32 s3, s3, 0
	s_mov_b32 s51, s72
	s_barrier
	s_cmp_ge_u32 s72, s78
	s_cbranch_scc0 .LBB0_2002
	s_and_b64 vcc, exec, s[68:69]
	s_cbranch_vccz .LBB0_2005
